# GEMM tile mapping: division/modulo by the group size (provably 8) done with shift and mask instead of the float-reciprocal idiom (9 sites)
# speedup vs baseline: 1.0194x; 1.0024x over previous
.LBB0_396:
	s_ashr_i32 s9, s9, 3
	s_add_i32 s9, s55, s9
	s_ashr_i32 s52, s9, 31
	s_lshr_b32 s52, s52, 27
	s_add_i32 s52, s9, s52
	s_ashr_i32 s53, s52, 5
	s_lshl_b32 s53, s53, 3
	s_sub_i32 s54, 64, s53
	s_min_i32 s54, s54, 8
	s_andn2_b32 s52, s52, 31
	s_sub_i32 s9, s9, s52
	s_abs_i32 s52, s9
	s_nop 0
	s_lshr_b32 s52, s9, 3
	s_and_b32 s9, s9, 7
	s_add_i32 s54, s53, s9

.LBB0_476:
	s_add_i32 s81, s69, 1
	s_mul_i32 s6, s81, s33
	s_mul_hi_u32 s7, s81, s1
	s_add_i32 s7, s7, s6
	s_mul_i32 s6, s81, s1
	s_add_u32 s62, s6, s10
	s_addc_u32 s63, s7, s79
	v_cmp_gt_i64_e32 vcc, s[62:63], v[148:149]
	v_cmp_lt_i64_e64 s[6:7], s[62:63], v[146:147]
	s_cbranch_vccnz .LBB0_478
	s_ashr_i32 s9, s62, 31
	s_lshr_b32 s9, s9, 29
	s_add_i32 s9, s62, s9
	s_ashr_i32 s58, s9, 3
	s_and_b32 s9, s9, -8
	s_sub_i32 s9, s62, s9
	s_cmp_lt_i32 s9, 0
	s_cselect_b32 s59, s75, 0x58
	s_mul_i32 s9, s59, s9
	s_add_i32 s9, s9, s58
	s_mul_hi_i32 s58, s9, 0x2e8ba2e9
	s_lshr_b32 s59, s58, 31
	s_ashr_i32 s58, s58, 4
	s_add_i32 s58, s58, s59
	s_lshl_b32 s59, s58, 3
	s_sub_i32 s60, 64, s59
	s_min_i32 s60, s60, 8
	s_mulk_i32 s58, 0x58
	s_sub_i32 s9, s9, s58
	s_abs_i32 s58, s9
	s_nop 0
	s_lshr_b32 s58, s9, 3
	s_and_b32 s9, s9, 7
	s_add_i32 s60, s9, s59

.LBB0_923:
	s_ashr_i32 s42, s44, 3
	s_add_i32 s42, s51, s42
	s_ashr_i32 s43, s42, 31
	s_lshr_b32 s43, s43, 27
	s_add_i32 s43, s42, s43
	s_ashr_i32 s44, s43, 5
	s_lshl_b32 s44, s44, 3
	s_sub_i32 s50, 64, s44
	s_min_i32 s50, s50, 8
	s_andn2_b32 s43, s43, 31
	s_sub_i32 s43, s42, s43
	s_abs_i32 s42, s43
	s_mul_i32 s45, s45, -3
	s_lshr_b32 s42, s43, 3
	s_and_b32 s43, s43, 7
	s_add_i32 s50, s44, s43
	s_add_i32 s44, s45, s75

.LBB0_1165:
	s_ashr_i32 s14, s14, 3
	s_add_i32 s14, s51, s14
	s_ashr_i32 s44, s14, 31
	s_lshr_b32 s44, s44, 27
	s_add_i32 s44, s14, s44
	s_ashr_i32 s45, s44, 5
	s_lshl_b32 s45, s45, 3
	s_sub_i32 s50, 64, s45
	s_min_i32 s50, s50, 8
	s_andn2_b32 s44, s44, 31
	s_sub_i32 s14, s14, s44
	s_abs_i32 s44, s14
	s_nop 0
	s_lshr_b32 s44, s14, 3
	s_and_b32 s14, s14, 7
	s_add_i32 s50, s45, s14

.LBB0_1470:
	s_andn2_b64 vcc, exec, s[48:49]
	s_cbranch_vccnz .LBB0_1474
	v_cmp_gt_i64_e32 vcc, s[44:45], v[196:197]
	s_mov_b64 s[50:51], 0
	s_cbranch_vccnz .LBB0_1473
	s_ashr_i32 s40, s44, 31
	s_lshr_b32 s40, s40, 29
	s_add_i32 s40, s44, s40
	s_ashr_i32 s41, s40, 3
	s_and_b32 s40, s40, -8
	s_sub_i32 s40, s44, s40
	s_cmp_lt_i32 s40, 0
	s_cselect_b32 s42, s3, 0xb0
	s_mul_i32 s40, s42, s40
	s_add_i32 s40, s40, s41
	s_mul_hi_i32 s41, s40, 0x2e8ba2e9
	s_lshr_b32 s42, s41, 31
	s_ashr_i32 s41, s41, 5
	s_add_i32 s41, s41, s42
	s_lshl_b32 s42, s41, 3
	s_sub_i32 s43, 64, s42
	s_min_i32 s43, s43, 8
	s_mulk_i32 s41, 0xb0
	s_sub_i32 s41, s40, s41
	s_abs_i32 s40, s41
	s_mov_b32 s92, 0
	s_lshr_b32 s40, s41, 3
	s_and_b32 s41, s41, 7
	s_add_i32 s42, s41, s42
	s_mov_b64 s[50:51], -1

.LBB0_2518:
	s_ashr_i32 s7, s7, 3
	s_add_i32 s7, s55, s7
	s_ashr_i32 s52, s7, 31
	s_lshr_b32 s52, s52, 27
	s_add_i32 s52, s7, s52
	s_ashr_i32 s53, s52, 5
	s_lshl_b32 s53, s53, 3
	s_sub_i32 s54, 64, s53
	s_min_i32 s54, s54, 8
	s_andn2_b32 s52, s52, 31
	s_sub_i32 s7, s7, s52
	s_abs_i32 s52, s7
	s_nop 0
	s_lshr_b32 s52, s7, 3
	s_and_b32 s7, s7, 7
	s_add_i32 s54, s53, s7

.LBB0_2599:
	s_add_i32 s84, s59, 1
	s_mul_i32 s4, s84, s33
	s_mul_hi_u32 s5, s84, s1
	s_add_i32 s5, s5, s4
	s_mul_i32 s4, s84, s1
	s_add_u32 s52, s4, s69
	s_addc_u32 s53, s5, s83
	v_cmp_gt_i64_e32 vcc, s[52:53], v[148:149]
	v_cmp_lt_i64_e64 s[4:5], s[52:53], v[146:147]
	s_cbranch_vccnz .LBB0_2601
	s_ashr_i32 s7, s52, 31
	s_lshr_b32 s7, s7, 29
	s_add_i32 s7, s52, s7
	s_ashr_i32 s44, s7, 3
	s_and_b32 s7, s7, -8
	s_sub_i32 s7, s52, s7
	s_cmp_lt_i32 s7, 0
	s_cselect_b32 s45, s3, 0x58
	s_mul_i32 s7, s45, s7
	s_add_i32 s7, s7, s44
	s_mul_hi_i32 s44, s7, 0x2e8ba2e9
	s_lshr_b32 s45, s44, 31
	s_ashr_i32 s44, s44, 4
	s_add_i32 s44, s44, s45
	s_lshl_b32 s45, s44, 3
	s_sub_i32 s50, 64, s45
	s_min_i32 s50, s50, 8
	s_mulk_i32 s44, 0x58
	s_sub_i32 s7, s7, s44
	s_abs_i32 s44, s7
	s_nop 0
	s_lshr_b32 s44, s7, 3
	s_and_b32 s7, s7, 7
	s_add_i32 s50, s7, s45

.LBB0_2983:
	s_ashr_i32 s42, s44, 3
	s_add_i32 s42, s51, s42
	s_ashr_i32 s43, s42, 31
	s_lshr_b32 s43, s43, 27
	s_add_i32 s43, s42, s43
	s_ashr_i32 s44, s43, 5
	s_lshl_b32 s44, s44, 3
	s_sub_i32 s50, 64, s44
	s_min_i32 s50, s50, 8
	s_andn2_b32 s43, s43, 31
	s_sub_i32 s43, s42, s43
	s_abs_i32 s42, s43
	s_mul_i32 s45, s45, -3
	s_lshr_b32 s42, s43, 3
	s_and_b32 s43, s43, 7
	s_add_i32 s50, s44, s43
	s_add_i32 s44, s45, s77

.LBB0_3225:
	s_ashr_i32 s14, s14, 3
	s_add_i32 s14, s45, s14
	s_ashr_i32 s42, s14, 31
	s_lshr_b32 s42, s42, 27
	s_add_i32 s42, s14, s42
	s_ashr_i32 s43, s42, 5
	s_lshl_b32 s43, s43, 3
	s_sub_i32 s44, 64, s43
	s_min_i32 s44, s44, 8
	s_andn2_b32 s42, s42, 31
	s_sub_i32 s14, s14, s42
	s_abs_i32 s42, s14
	s_nop 0
	s_lshr_b32 s42, s14, 3
	s_and_b32 s14, s14, 7
	s_add_i32 s44, s43, s14
